# attn: 4-buffer KV LDS ring, 1 barrier per tile, ds_write overlapped with PV
# speedup vs baseline: 1.0291x; 1.0290x over previous
.LBB0_397:
	s_and_b32 s45, s0, 15
	s_ashr_i32 s37, s36, 31
	s_mul_i32 s3, s36, 0x1800
	s_mul_hi_i32 s1, s36, 0x1800
	s_add_u32 s3, s78, s3
	v_readlane_b32 s2, v252, 50
	s_addc_u32 s1, s2, s1
	s_lshl_b32 s5, s45, 7
	s_add_u32 s30, s3, s5
	s_addc_u32 s31, s1, 0
	v_readlane_b32 s2, v250, 19
	v_readlane_b32 s3, v250, 20
	s_add_u32 s28, s2, s5
	v_mov_b32_e32 v6, v168
	s_addc_u32 s29, s3, 0
	s_lshl_b32 s0, s0, 7
	s_and_b32 s0, s0, 0x700
	v_ashrrev_i32_e32 v0, 6, v6
	v_and_b32_e32 v62, 63, v6
	v_and_b32_e32 v1, 0x3fffffc0, v6
	v_and_b32_e32 v200, 31, v6
	v_lshl_add_u32 v175, v1, 2, v192
	v_lshl_add_u32 v1, v0, 12, v192
	v_lshlrev_b32_e32 v7, 4, v62
	v_lshlrev_b32_e32 v174, 5, v0
	s_add_u32 s39, s73, s0
	v_bfe_u32 v201, v6, 5, 1
	v_add_u32_e32 v204, v1, v7
	v_or_b32_e32 v2, v174, v200
	v_mov_b64_e32 v[0:1], s[30:31]
	s_movk_i32 s0, 0x1800
	v_mad_i64_i32 v[0:1], s[0:1], v2, s0, v[0:1]
	v_lshlrev_b32_e32 v176, 4, v201
	v_mov_b32_e32 v177, v171
	v_lshl_add_u64 v[4:5], v[0:1], 0, v[176:177]
	global_load_dwordx4 v[0:3], v[4:5], off
	v_lshlrev_b32_e32 v12, 3, v6
	s_movk_i32 s1, 0xe0
	s_mov_b32 s0, 0x7ffffc
	s_addc_u32 s42, s63, 0
	s_cmp_lg_u32 0x100, -1
	s_mul_i32 s44, s38, 0x1800
	s_mul_hi_i32 s43, s38, 0x1800
	v_and_b32_e32 v8, 0x70, v6
	v_lshlrev_b32_e32 v72, 7, v200
	v_and_b32_e32 v73, 0x70, v12
	v_or_b32_e32 v64, 32, v176
	v_bitop3_b32 v64, v64, v72, v73 bitop3:0xde
	v_add_u32_e32 v209, 0x100, v64
	s_mov_b32 s5, s4
	s_mov_b32 s10, s4
	s_mov_b32 s11, s4
	s_mov_b32 s12, s4
	s_mov_b32 s13, s4
	s_mov_b32 s14, s4
	s_mov_b32 s15, s4
	s_mov_b32 s16, s4
	s_mov_b32 s17, s4
	s_mov_b32 s18, s4
	s_mov_b32 s19, s4
	v_mov_b32_e32 v61, v171
	v_cmp_gt_u32_e64 s[40:41], 32, v62
	s_mov_b32 s50, 4
	s_movk_i32 s51, 0xc0
	v_lshl_add_u32 v177, v200, 2, v175
	v_mov_b32_e32 v178, 0
	s_waitcnt vmcnt(0)
	ds_write_b128 v204, v[0:3] offset:51200
	global_load_dwordx4 v[0:3], v[4:5], off offset:32
	s_waitcnt vmcnt(0)
	ds_write_b128 v204, v[0:3] offset:52224
	global_load_dwordx4 v[0:3], v[4:5], off offset:64
	s_waitcnt vmcnt(0)
	ds_write_b128 v204, v[0:3] offset:53248
	global_load_dwordx4 v[0:3], v[4:5], off offset:96
	v_and_b32_e32 v5, 24, v12
	s_waitcnt vmcnt(0)
	ds_write_b128 v204, v[0:3] offset:54272
	v_ashrrev_i32_e32 v0, 4, v6
	v_lshlrev_b32_e32 v4, 5, v0
	v_lshrrev_b32_e32 v2, 5, v6
	v_bfe_u32 v3, v12, 5, 2
	v_and_or_b32 v4, v4, s1, v5
	v_and_or_b32 v2, v2, s0, v3
	v_lshlrev_b32_e32 v4, 1, v4
	v_lshl_or_b32 v13, v2, 9, v4
	v_add_u32_e32 v2, 32, v0
	v_lshrrev_b32_e32 v2, 1, v2
	v_and_or_b32 v2, v2, s0, v3
	s_movk_i32 s0, 0xc00
	v_and_b32_e32 v1, 0x78, v12
	v_mul_lo_u32 v0, v0, s0
	v_lshl_or_b32 v14, v2, 9, v4
	v_ashrrev_i32_e32 v2, 3, v6
	v_or_b32_e32 v0, v0, v1
	v_and_b32_e32 v3, 56, v12
	v_lshlrev_b32_e32 v170, 1, v0
	v_mul_lo_u32 v0, v2, s0
	v_or_b32_e32 v0, v0, v3
	s_cselect_b32 s0, 0x100, 0
	s_add_u32 s6, s39, s44
	v_lshlrev_b32_e32 v4, 7, v2
	v_lshlrev_b32_e32 v5, 1, v3
	v_lshlrev_b32_e32 v60, 1, v0
	v_lshlrev_b32_e32 v0, 3, v62
	v_and_b32_e32 v1, 0xc0, v7
	v_lshlrev_b32_e32 v2, 1, v6
	s_addc_u32 s7, s42, s43
	v_bitop3_b32 v15, v5, v4, v8 bitop3:0xde
	v_and_or_b32 v1, v0, 24, v1
	v_and_b32_e32 v2, 32, v2
	v_and_b32_e32 v0, 0x100, v0
	v_lshl_add_u64 v[4:5], s[6:7], 0, v[170:171]
	v_or3_b32 v63, v1, v2, v0
	s_add_u32 s8, s28, s44
	global_load_dwordx4 v[0:3], v170, s[6:7]
	v_add_co_u32_e32 v4, vcc, s33, v4
	s_addc_u32 s9, s29, s43
	s_nop 0
	v_addc_co_u32_e32 v5, vcc, 0, v5, vcc
	global_load_dwordx4 v[4:7], v[4:5], off
	v_add_u32_e32 v205, 0x100, v13
	global_load_dwordx4 v[8:11], v60, s[8:9]
	s_waitcnt vmcnt(0)
	v_add_u32_e32 v206, 0x100, v14
	v_add_u32_e32 v207, 0x100, v15
	s_mov_b32 s6, s4
	s_mov_b32 s7, s4
	s_mov_b32 s8, s4
	s_mov_b32 s9, s4
	s_add_i32 s1, s38, 64
	v_add_u32_e32 v203, s0, v63
	v_lshl_add_u64 v[180:181], s[28:29], 0, v[60:61]
	s_waitcnt vmcnt(2)
	ds_write_b128 v205, v[0:3]
	v_bitop3_b32 v0, v176, v72, v73 bitop3:0xde
	v_add_u32_e32 v208, 0x100, v0
	s_waitcnt vmcnt(1)
	ds_write_b128 v206, v[4:7]
	s_waitcnt vmcnt(0)
	ds_write_b128 v207, v[8:11] offset:32768
	s_waitcnt lgkmcnt(0)
	s_barrier
	ds_read_b128 v[56:59], v204 offset:52224
	ds_read_b128 v[52:55], v204 offset:53248
	ds_read_b128 v[48:51], v204 offset:54272
	ds_read_b128 v[16:19], v208 offset:36864
	ds_read_b128 v[20:23], v208 offset:32768
	ds_read_b128 v[24:27], v204 offset:51200
	s_waitcnt lgkmcnt(0)
	v_mfma_f32_32x32x16_bf16 v[32:47], v[20:23], v[24:27], 0
	ds_read_b128 v[64:67], v209 offset:36864
	ds_read_b128 v[68:71], v209 offset:32768
	v_mov_b64_e32 v[0:1], s[4:5]
	v_mov_b64_e32 v[2:3], s[6:7]
	v_mov_b64_e32 v[4:5], s[8:9]
	v_mov_b64_e32 v[6:7], s[10:11]
	v_mov_b64_e32 v[8:9], s[12:13]
	v_mov_b64_e32 v[10:11], s[14:15]
	v_mfma_f32_32x32x16_bf16 v[16:31], v[16:19], v[24:27], 0
	v_mov_b64_e32 v[12:13], s[16:17]
	v_mov_b64_e32 v[14:15], s[18:19]
	s_add_i32 s12, s44, 0x60000
	s_mul_hi_i32 s5, s1, 0x1800
	s_add_u32 s6, s39, s12
	s_addc_u32 s7, s42, s5
	s_add_u32 s8, s28, s12
	s_waitcnt lgkmcnt(0)
	v_mfma_f32_32x32x16_bf16 v[32:47], v[68:71], v[56:59], v[32:47]
	s_addc_u32 s9, s29, s5
	s_add_i32 s1, s38, 0x80
	s_add_i32 s47, s44, 0xc0000
	s_mul_hi_i32 s46, s1, 0x1800
	v_mfma_f32_32x32x16_bf16 v[16:31], v[64:67], v[56:59], v[16:31]
	v_or_b32_e32 v56, 64, v176
	v_bitop3_b32 v56, v56, v72, v73 bitop3:0xde
	v_add_u32_e32 v210, 0x100, v56
	ds_read_b128 v[56:59], v210 offset:36864
	ds_read_b128 v[64:67], v210 offset:32768
	s_waitcnt lgkmcnt(0)
	v_mfma_f32_32x32x16_bf16 v[32:47], v[64:67], v[52:55], v[32:47]
	v_mfma_f32_32x32x16_bf16 v[16:31], v[56:59], v[52:55], v[16:31]
	v_or_b32_e32 v52, 0x60, v176
	v_bitop3_b32 v52, v52, v72, v73 bitop3:0xde
	v_add_u32_e32 v211, 0x100, v52
	ds_read_b128 v[52:55], v211 offset:36864
	ds_read_b128 v[56:59], v211 offset:32768
	s_waitcnt lgkmcnt(0)
	v_mfma_f32_32x32x16_bf16 v[32:47], v[56:59], v[48:51], v[32:47]
	v_mfma_f32_32x32x16_bf16 v[16:31], v[52:55], v[48:51], v[16:31]
	s_nop 10
	v_max_f32_e32 v48, v33, v33
	v_max_f32_e32 v49, v32, v32
	v_max_f32_e32 v48, v49, v48
	v_max3_f32 v48, v48, v34, v35
	v_max3_f32 v48, v48, v36, v37
	v_max3_f32 v48, v48, v38, v39
	v_max3_f32 v48, v48, v40, v41
	v_max3_f32 v48, v48, v42, v43
	v_max3_f32 v48, v48, v44, v45
	v_max3_f32 v48, v48, v46, v47
	v_max3_f32 v48, v48, v16, v17
	v_max3_f32 v48, v48, v18, v19
	v_max3_f32 v48, v48, v20, v21
	v_max3_f32 v48, v48, v22, v23
	v_max3_f32 v48, v48, v24, v25
	v_max3_f32 v48, v48, v26, v27
	v_max3_f32 v48, v48, v28, v29
	v_max3_f32 v48, v48, v30, v31
	v_mov_b32_e32 v49, v48
	s_nop 1
	v_permlane32_swap_b32_e32 v48, v49
	v_max_f32_e32 v49, v49, v49
	v_max_f32_e32 v48, v48, v48
	v_max_f32_e32 v48, v48, v49
	v_sub_f32_e32 v36, v36, v48
	v_sub_f32_e32 v37, v37, v48
	v_exp_f32_e32 v53, v36
	v_exp_f32_e32 v54, v37
	v_lshl_add_u64 v[36:37], s[6:7], 0, v[170:171]
	v_add_co_u32_e32 v36, vcc, s33, v36
	v_sub_f32_e32 v32, v32, v48
	v_sub_f32_e32 v33, v33, v48
	v_sub_f32_e32 v34, v34, v48
	v_sub_f32_e32 v35, v35, v48
	v_sub_f32_e32 v38, v38, v48
	v_sub_f32_e32 v39, v39, v48
	v_sub_f32_e32 v40, v40, v48
	v_sub_f32_e32 v41, v41, v48
	v_sub_f32_e32 v42, v42, v48
	v_sub_f32_e32 v43, v43, v48
	v_sub_f32_e32 v44, v44, v48
	v_sub_f32_e32 v45, v45, v48
	v_sub_f32_e32 v46, v46, v48
	v_sub_f32_e32 v47, v47, v48
	v_addc_co_u32_e32 v37, vcc, 0, v37, vcc
	v_exp_f32_e32 v49, v32
	v_exp_f32_e32 v50, v33
	v_exp_f32_e32 v51, v34
	v_exp_f32_e32 v52, v35
	v_exp_f32_e32 v55, v38
	v_exp_f32_e32 v56, v39
	v_exp_f32_e32 v57, v40
	v_exp_f32_e32 v58, v41
	v_exp_f32_e32 v59, v42
	v_exp_f32_e32 v64, v43
	v_exp_f32_e32 v65, v44
	v_exp_f32_e32 v66, v45
	v_exp_f32_e32 v46, v46
	v_exp_f32_e32 v47, v47
	v_cvt_pk_bf16_f32 v144, v49, v50
	v_cvt_pk_bf16_f32 v145, v51, v52
	v_cvt_pk_bf16_f32 v146, v53, v54
	v_cvt_pk_bf16_f32 v147, v55, v56
	v_cvt_pk_bf16_f32 v140, v57, v58
	v_cvt_pk_bf16_f32 v141, v59, v64
	v_cvt_pk_bf16_f32 v142, v65, v66
	v_cvt_pk_bf16_f32 v143, v46, v47
	global_load_dwordx4 v[32:35], v170, s[6:7]
	s_nop 0
	global_load_dwordx4 v[36:39], v[36:37], off
	s_nop 0
	global_load_dwordx4 v[40:43], v60, s[8:9]
	s_add_u32 s6, s28, s47
	s_addc_u32 s7, s29, s46
	global_load_dwordx4 v[128:131], v60, s[6:7]
	s_add_u32 s6, s39, s47
	s_addc_u32 s7, s42, s46
	v_lshl_add_u64 v[44:45], s[6:7], 0, v[170:171]
	v_add_co_u32_e32 v44, vcc, s33, v44
	v_add_f32_e32 v212, 0, v48
	s_nop 0
	v_addc_co_u32_e32 v45, vcc, 0, v45, vcc
	global_load_dwordx4 v[136:139], v[44:45], off
	global_load_dwordx4 v[132:135], v170, s[6:7]
	s_waitcnt vmcnt(3)
	s_waitcnt vmcnt(5)
	ds_write_b128 v205, v[32:35] offset:16384
	s_waitcnt vmcnt(4)
	ds_write_b128 v206, v[36:39] offset:16384
	s_waitcnt vmcnt(3)
	ds_write_b128 v207, v[40:43] offset:40960
	v_add_f32_e32 v32, 0, v49
	v_add_f32_e32 v32, v50, v32
	v_add_f32_e32 v32, v51, v32
	v_add_f32_e32 v32, v52, v32
	v_add_f32_e32 v32, v53, v32
	v_add_f32_e32 v32, v54, v32
	v_add_f32_e32 v32, v55, v32
	v_add_f32_e32 v32, v56, v32
	v_add_f32_e32 v32, v57, v32
	v_add_f32_e32 v32, v58, v32
	v_add_f32_e32 v32, v59, v32
	v_add_f32_e32 v32, v64, v32
	v_add_f32_e32 v32, v65, v32
	v_add_f32_e32 v32, v66, v32
	v_add_f32_e32 v32, v46, v32
	s_addk_i32 s0, 0x4000
	v_xor_b32_e32 v96, 0x80000000, v212
	v_add_f32_e32 v164, v47, v32
	v_sub_f32_e32 v95, v31, v48
	v_sub_f32_e32 v94, v30, v48
	v_sub_f32_e32 v93, v29, v48
	v_sub_f32_e32 v92, v28, v48
	v_sub_f32_e32 v91, v27, v48
	v_sub_f32_e32 v90, v26, v48
	v_sub_f32_e32 v89, v25, v48
	v_sub_f32_e32 v88, v24, v48
	v_sub_f32_e32 v87, v23, v48
	v_sub_f32_e32 v86, v22, v48
	v_sub_f32_e32 v85, v21, v48
	v_sub_f32_e32 v84, v20, v48
	v_sub_f32_e32 v83, v19, v48
	v_sub_f32_e32 v82, v18, v48
	v_sub_f32_e32 v81, v17, v48
	v_sub_f32_e32 v80, v16, v48
	v_add_u32_e32 v202, s0, v63
	v_mov_b64_e32 v[62:63], v[14:15]
	v_mov_b64_e32 v[46:47], v[14:15]
	v_mov_b64_e32 v[30:31], v[14:15]
	s_mov_b64 s[8:9], 0
	v_mov_b64_e32 v[60:61], v[12:13]
	v_mov_b64_e32 v[58:59], v[10:11]
	v_mov_b64_e32 v[56:57], v[8:9]
	v_mov_b64_e32 v[54:55], v[6:7]
	v_mov_b64_e32 v[52:53], v[4:5]
	v_mov_b64_e32 v[50:51], v[2:3]
	v_mov_b64_e32 v[48:49], v[0:1]
	v_mov_b64_e32 v[44:45], v[12:13]
	v_mov_b64_e32 v[42:43], v[10:11]
	v_mov_b64_e32 v[40:41], v[8:9]
	v_mov_b64_e32 v[38:39], v[6:7]
	v_mov_b64_e32 v[36:37], v[4:5]
	v_mov_b64_e32 v[34:35], v[2:3]
	v_mov_b64_e32 v[32:33], v[0:1]
	v_mov_b64_e32 v[28:29], v[12:13]
	v_mov_b64_e32 v[26:27], v[10:11]
	v_mov_b64_e32 v[24:25], v[8:9]
	v_mov_b64_e32 v[22:23], v[6:7]
	v_mov_b64_e32 v[20:21], v[4:5]
	v_mov_b64_e32 v[18:19], v[2:3]
	v_mov_b64_e32 v[16:17], v[0:1]
	v_mov_b32_e32 v97, v96
	v_mov_b32_e32 v98, v96
	v_mov_b32_e32 v99, v96
	v_mov_b32_e32 v100, v96
	v_mov_b32_e32 v101, v96
	v_mov_b32_e32 v102, v96
	v_mov_b32_e32 v103, v96
	v_mov_b32_e32 v104, v96
	v_mov_b32_e32 v105, v96
	v_mov_b32_e32 v106, v96
	v_mov_b32_e32 v107, v96
	v_mov_b32_e32 v108, v96
	v_mov_b32_e32 v109, v96
	v_mov_b32_e32 v110, v96
	v_mov_b32_e32 v111, v96
	s_waitcnt lgkmcnt(0)
	s_barrier
	s_mov_b32 s100, 0x14800
	s_mov_b32 s101, 0x18010
	v_add_u32_e32 v205, s100, v205
	v_add_u32_e32 v206, s100, v206
	v_add_u32_e32 v207, s101, v207

.LBB0_400:
	v_cvt_pk_bf16_f32 v182, v148, v149
	v_cvt_pk_bf16_f32 v183, v152, v153
	v_cvt_pk_bf16_f32 v184, v154, v155
	v_cvt_pk_bf16_f32 v185, v158, v159
	v_cvt_pk_bf16_f32 v160, v150, v151
	v_cvt_pk_bf16_f32 v161, v156, v157
	v_cvt_pk_bf16_f32 v162, v162, v163
	v_cvt_pk_bf16_f32 v163, v166, v167
	s_waitcnt vmcnt(0)
	ds_write_b128 v205, v[132:135]
	ds_write_b128 v206, v[136:139]
	ds_write_b128 v207, v[128:131] offset:32768
	s_cmpk_lt_u32 s51, 0x100
	s_cselect_b32 s0, s38, s34
	s_add_i32 s3, s0, s51
	s_mul_i32 s0, s3, 0x1800
	s_mul_hi_i32 s1, s3, 0x1800
	s_add_u32 s0, s39, s0
	s_addc_u32 s1, s42, s1
	v_lshl_add_u64 v[148:149], s[0:1], 0, v[170:171]
	v_add_co_u32_e32 v152, vcc, s33, v148
	v_mad_i64_i32 v[156:157], s[0:1], s3, v195, v[180:181]
	s_nop 0
	v_addc_co_u32_e32 v153, vcc, 0, v149, vcc
	global_load_dwordx4 v[148:151], v[148:149], off
	s_nop 0
	global_load_dwordx4 v[152:155], v[152:153], off
	s_nop 0
	global_load_dwordx4 v[156:159], v[156:157], off
	ds_read_b64_tr_b16 v[186:187], v203 offset:0
	ds_read_b64_tr_b16 v[188:189], v203 offset:0x800
	ds_read_b64_tr_b16 v[214:215], v203 offset:0x200
	ds_read_b64_tr_b16 v[216:217], v203 offset:0xa00
	ds_read_b64_tr_b16 v[218:219], v203 offset:0x400
	ds_read_b64_tr_b16 v[220:221], v203 offset:0xc00
	ds_read_b64_tr_b16 v[222:223], v203 offset:0x600
	ds_read_b64_tr_b16 v[224:225], v203 offset:0xe00
	ds_read_b64_tr_b16 v[226:227], v203 offset:0x1000
	ds_read_b64_tr_b16 v[228:229], v203 offset:0x1800
	ds_read_b64_tr_b16 v[230:231], v203 offset:0x1200
	ds_read_b64_tr_b16 v[232:233], v203 offset:0x1a00
	ds_read_b64_tr_b16 v[234:235], v203 offset:0x1400
	ds_read_b64_tr_b16 v[236:237], v203 offset:0x1c00
	ds_read_b64_tr_b16 v[238:239], v203 offset:0x1600
	ds_read_b64_tr_b16 v[240:241], v203 offset:0x1e00
	s_nop 0
	s_waitcnt lgkmcnt(8)
	v_exp_f32_e32 v112, v112
	v_mfma_f32_32x32x16_bf16 v[0:15], v[144:147], v[186:189], v[0:15]
	v_exp_f32_e32 v113, v113
	v_exp_f32_e32 v114, v114
	v_exp_f32_e32 v115, v115
	v_exp_f32_e32 v116, v116
	v_exp_f32_e32 v117, v117
	v_exp_f32_e32 v118, v118
	v_exp_f32_e32 v119, v119
	v_mfma_f32_32x32x16_bf16 v[48:63], v[144:147], v[214:217], v[48:63]
	v_exp_f32_e32 v120, v120
	v_exp_f32_e32 v121, v121
	v_exp_f32_e32 v122, v122
	v_exp_f32_e32 v123, v123
	v_exp_f32_e32 v124, v124
	v_exp_f32_e32 v125, v125
	v_exp_f32_e32 v126, v126
	v_mfma_f32_32x32x16_bf16 v[32:47], v[144:147], v[218:221], v[32:47]
	v_exp_f32_e32 v127, v127
	v_mfma_f32_32x32x16_bf16 v[16:31], v[144:147], v[222:225], v[16:31]
	ds_read_b64_tr_b16 v[144:145], v203 offset:0x2000
	ds_read_b64_tr_b16 v[146:147], v203 offset:0x2800
	ds_read_b64_tr_b16 v[186:187], v203 offset:0x2200
	ds_read_b64_tr_b16 v[188:189], v203 offset:0x2a00
	ds_read_b64_tr_b16 v[214:215], v203 offset:0x2400
	ds_read_b64_tr_b16 v[216:217], v203 offset:0x2c00
	ds_read_b64_tr_b16 v[218:219], v203 offset:0x2600
	ds_read_b64_tr_b16 v[220:221], v203 offset:0x2e00
	s_waitcnt lgkmcnt(8)
	ds_read_b64_tr_b16 v[222:223], v203 offset:0x3000
	ds_read_b64_tr_b16 v[224:225], v203 offset:0x3800
	s_nop 0
	v_mfma_f32_32x32x16_bf16 v[0:15], v[140:143], v[226:229], v[0:15]
	ds_read_b64_tr_b16 v[226:227], v203 offset:0x3200
	ds_read_b64_tr_b16 v[228:229], v203 offset:0x3a00
	v_mfma_f32_32x32x16_bf16 v[48:63], v[140:143], v[230:233], v[48:63]
	ds_read_b64_tr_b16 v[230:231], v203 offset:0x3400
	ds_read_b64_tr_b16 v[232:233], v203 offset:0x3c00
	v_mfma_f32_32x32x16_bf16 v[32:47], v[140:143], v[234:237], v[32:47]
	ds_read_b64_tr_b16 v[234:235], v203 offset:0x3600
	ds_read_b64_tr_b16 v[236:237], v203 offset:0x3e00
	s_waitcnt lgkmcnt(8)
	s_nop 0
	s_waitcnt lgkmcnt(0)
	v_mfma_f32_32x32x16_bf16 v[16:31], v[140:143], v[238:241], v[16:31]
	v_add_f32_e32 v140, 0, v112
	v_add_f32_e32 v140, v113, v140
	v_add_f32_e32 v140, v114, v140
	v_add_f32_e32 v140, v115, v140
	v_add_f32_e32 v140, v116, v140
	v_add_f32_e32 v140, v117, v140
	v_add_f32_e32 v140, v118, v140
	v_mfma_f32_32x32x16_bf16 v[0:15], v[182:185], v[144:147], v[0:15]
	v_add_f32_e32 v140, v119, v140
	v_add_f32_e32 v140, v120, v140
	v_add_f32_e32 v140, v121, v140
	v_add_f32_e32 v140, v122, v140
	v_add_f32_e32 v140, v123, v140
	v_add_f32_e32 v140, v124, v140
	v_add_f32_e32 v140, v125, v140
	v_mfma_f32_32x32x16_bf16 v[48:63], v[182:185], v[186:189], v[48:63]
	v_add_f32_e32 v140, v126, v140
	v_add_f32_e32 v165, v127, v140
	v_cvt_pk_bf16_f32 v144, v112, v113
	v_cvt_pk_bf16_f32 v145, v114, v115
	v_cvt_pk_bf16_f32 v146, v116, v117
	v_cvt_pk_bf16_f32 v147, v118, v119
	v_cvt_pk_bf16_f32 v140, v120, v121
	v_mfma_f32_32x32x16_bf16 v[32:47], v[182:185], v[214:217], v[32:47]
	v_cvt_pk_bf16_f32 v141, v122, v123
	v_cvt_pk_bf16_f32 v142, v124, v125
	v_cvt_pk_bf16_f32 v143, v126, v127
	v_mfma_f32_32x32x16_bf16 v[16:31], v[182:185], v[218:221], v[16:31]
	s_waitcnt lgkmcnt(0)
	s_barrier
	v_mfma_f32_32x32x16_bf16 v[0:15], v[160:163], v[222:225], v[0:15]
	v_mfma_f32_32x32x16_bf16 v[48:63], v[160:163], v[226:229], v[48:63]
	v_mfma_f32_32x32x16_bf16 v[32:47], v[160:163], v[230:233], v[32:47]
	v_mfma_f32_32x32x16_bf16 v[16:31], v[160:163], v[234:237], v[16:31]
	v_add_u32_e32 v208, s101, v208
	v_add_u32_e32 v209, s101, v209
	v_add_u32_e32 v210, s101, v210
	v_add_u32_e32 v211, s101, v211
	ds_read_b128 v[160:163], v208 offset:32768
	ds_read_b128 v[214:217], v204 offset:51200
	ds_read_b128 v[218:221], v204 offset:52224
	ds_read_b128 v[222:225], v208 offset:36864
	v_exp_f32_e32 v166, v84
	v_exp_f32_e32 v167, v85
	s_waitcnt lgkmcnt(2)
	v_mfma_f32_32x32x16_bf16 v[112:127], v[160:163], v[214:217], v[64:79]
	ds_read_b128 v[160:163], v209 offset:32768
	ds_read_b128 v[226:229], v209 offset:36864
	ds_read_b128 v[230:233], v204 offset:53248
	ds_read_b128 v[234:237], v204 offset:54272
	ds_read_b128 v[238:241], v210 offset:36864
	ds_read_b128 v[182:185], v210 offset:32768
	ds_read_b128 v[242:245], v211 offset:36864
	ds_read_b128 v[188:191], v211 offset:32768
	v_exp_f32_e32 v186, v90
	v_exp_f32_e32 v187, v91
	s_andn2_b64 s[0:1], s[6:7], exec
	s_and_b64 s[6:7], s[8:9], exec
	s_or_b64 s[6:7], s[0:1], s[6:7]
	s_waitcnt lgkmcnt(7)
	v_mfma_f32_32x32x16_bf16 v[112:127], v[160:163], v[218:221], v[112:127]
	v_exp_f32_e32 v160, v80
	v_exp_f32_e32 v161, v81
	v_exp_f32_e32 v162, v82
	v_exp_f32_e32 v163, v83
	v_add_f32_e32 v80, v160, v165
	v_add_f32_e32 v80, v161, v80
	v_add_f32_e32 v165, v162, v80
	s_waitcnt lgkmcnt(2)
	v_mfma_f32_32x32x16_bf16 v[112:127], v[182:185], v[230:233], v[112:127]
	v_exp_f32_e32 v182, v86
	v_exp_f32_e32 v183, v87
	v_exp_f32_e32 v184, v88
	v_exp_f32_e32 v185, v89
	v_add_f32_e32 v165, v163, v165
	v_add_f32_e32 v165, v166, v165
	v_add_f32_e32 v165, v167, v165
	s_waitcnt lgkmcnt(0)
	v_mfma_f32_32x32x16_bf16 v[112:127], v[188:191], v[234:237], v[112:127]
	v_exp_f32_e32 v188, v92
	v_exp_f32_e32 v189, v93
	v_exp_f32_e32 v190, v94
	v_exp_f32_e32 v191, v95
	v_add_f32_e32 v165, v182, v165
	v_add_f32_e32 v165, v183, v165
	v_add_f32_e32 v165, v184, v165
	v_mfma_f32_32x32x16_bf16 v[80:95], v[222:225], v[214:217], v[64:79]
	v_add_f32_e32 v165, v185, v165
	v_add_f32_e32 v165, v186, v165
	v_add_f32_e32 v165, v187, v165
	v_add_f32_e32 v165, v188, v165
	v_add_f32_e32 v165, v189, v165
	v_add_f32_e32 v165, v190, v165
	v_add_f32_e32 v165, v191, v165
	v_mfma_f32_32x32x16_bf16 v[80:95], v[226:229], v[218:221], v[80:95]
	v_mov_b32_e32 v179, v165
	s_nop 1
	v_permlane32_swap_b32_e32 v165, v179
	v_add_f32_e64 v178, v164, v178
	v_add_f32_e64 v179, v165, v179
	v_cmp_ge_f32_e32 vcc, s99, v179
	s_cmp_eq_u64 vcc, exec
	v_mfma_f32_32x32x16_bf16 v[80:95], v[238:241], v[230:233], v[80:95]
	v_mfma_f32_32x32x16_bf16 v[80:95], v[242:245], v[234:237], v[80:95]
	s_cbranch_scc0 .LBB0_408
.LBB0_401:
	v_cvt_pk_bf16_f32 v164, v160, v161
	v_cvt_pk_bf16_f32 v165, v162, v163
	v_cvt_pk_bf16_f32 v166, v166, v167
	v_cvt_pk_bf16_f32 v167, v182, v183
	v_cvt_pk_bf16_f32 v160, v184, v185
	v_cvt_pk_bf16_f32 v161, v186, v187
	v_cvt_pk_bf16_f32 v162, v188, v189
	v_cvt_pk_bf16_f32 v163, v190, v191
	s_waitcnt vmcnt(0)
	ds_write_b128 v205, v[148:151] offset:16384
	ds_write_b128 v206, v[152:155] offset:16384
	ds_write_b128 v207, v[156:159] offset:40960
	s_cmp_ge_u32 s50, s35
	s_cselect_b64 s[8:9], -1, 0
	s_and_b64 vcc, exec, s[8:9]
	s_cbranch_vccnz .LBB0_403
	s_add_i32 s0, s34, s51
	s_add_i32 s3, s0, 64
	s_mul_i32 s0, s3, 0x1800
	s_mul_hi_i32 s1, s3, 0x1800
	s_add_u32 s0, s39, s0
	s_addc_u32 s1, s42, s1
	v_lshl_add_u64 v[128:129], s[0:1], 0, v[170:171]
	v_add_co_u32_e32 v130, vcc, 0x30000, v128
	s_nop 1
	v_addc_co_u32_e32 v131, vcc, 0, v129, vcc
	global_load_dwordx4 v[132:135], v[128:129], off
	global_load_dwordx4 v[136:139], v[130:131], off
	v_mad_i64_i32 v[128:129], s[0:1], s3, v195, v[180:181]
	global_load_dwordx4 v[128:131], v[128:129], off
.LBB0_403:
	v_add_f32_e32 v178, v179, v178
	ds_read_b64_tr_b16 v[182:183], v202 offset:0
	ds_read_b64_tr_b16 v[184:185], v202 offset:0x800
	ds_read_b64_tr_b16 v[186:187], v202 offset:0x200
	ds_read_b64_tr_b16 v[188:189], v202 offset:0xa00
	ds_read_b64_tr_b16 v[214:215], v202 offset:0x400
	ds_read_b64_tr_b16 v[216:217], v202 offset:0xc00
	ds_read_b64_tr_b16 v[218:219], v202 offset:0x600
	ds_read_b64_tr_b16 v[220:221], v202 offset:0xe00
	ds_read_b64_tr_b16 v[222:223], v202 offset:0x1000
	ds_read_b64_tr_b16 v[224:225], v202 offset:0x1800
	ds_read_b64_tr_b16 v[226:227], v202 offset:0x1200
	ds_read_b64_tr_b16 v[228:229], v202 offset:0x1a00
	ds_read_b64_tr_b16 v[230:231], v202 offset:0x1400
	ds_read_b64_tr_b16 v[232:233], v202 offset:0x1c00
	ds_read_b64_tr_b16 v[234:235], v202 offset:0x1600
	ds_read_b64_tr_b16 v[236:237], v202 offset:0x1e00
	s_nop 0
	s_waitcnt lgkmcnt(8)
	v_exp_f32_e32 v112, v112
	v_mfma_f32_32x32x16_bf16 v[0:15], v[144:147], v[182:185], v[0:15]
	v_exp_f32_e32 v113, v113
	v_exp_f32_e32 v114, v114
	v_exp_f32_e32 v115, v115
	v_exp_f32_e32 v116, v116
	v_exp_f32_e32 v117, v117
	v_exp_f32_e32 v118, v118
	v_exp_f32_e32 v119, v119
	v_mfma_f32_32x32x16_bf16 v[48:63], v[144:147], v[186:189], v[48:63]
	v_exp_f32_e32 v120, v120
	v_exp_f32_e32 v121, v121
	v_exp_f32_e32 v122, v122
	v_exp_f32_e32 v123, v123
	v_exp_f32_e32 v124, v124
	v_exp_f32_e32 v125, v125
	v_exp_f32_e32 v126, v126
	v_mfma_f32_32x32x16_bf16 v[32:47], v[144:147], v[214:217], v[32:47]
	v_exp_f32_e32 v127, v127
	s_addk_i32 s51, 0x80
	s_add_i32 s50, s50, 2
	s_and_b64 vcc, exec, s[8:9]
	v_mfma_f32_32x32x16_bf16 v[16:31], v[144:147], v[218:221], v[16:31]
	ds_read_b64_tr_b16 v[144:145], v202 offset:0x2000
	ds_read_b64_tr_b16 v[146:147], v202 offset:0x2800
	ds_read_b64_tr_b16 v[182:183], v202 offset:0x2200
	ds_read_b64_tr_b16 v[184:185], v202 offset:0x2a00
	ds_read_b64_tr_b16 v[186:187], v202 offset:0x2400
	ds_read_b64_tr_b16 v[188:189], v202 offset:0x2c00
	ds_read_b64_tr_b16 v[214:215], v202 offset:0x2600
	ds_read_b64_tr_b16 v[216:217], v202 offset:0x2e00
	s_waitcnt lgkmcnt(8)
	ds_read_b64_tr_b16 v[218:219], v202 offset:0x3000
	ds_read_b64_tr_b16 v[220:221], v202 offset:0x3800
	s_nop 0
	v_mfma_f32_32x32x16_bf16 v[0:15], v[140:143], v[222:225], v[0:15]
	ds_read_b64_tr_b16 v[222:223], v202 offset:0x3200
	ds_read_b64_tr_b16 v[224:225], v202 offset:0x3a00
	v_mfma_f32_32x32x16_bf16 v[48:63], v[140:143], v[226:229], v[48:63]
	ds_read_b64_tr_b16 v[226:227], v202 offset:0x3400
	ds_read_b64_tr_b16 v[228:229], v202 offset:0x3c00
	v_mfma_f32_32x32x16_bf16 v[32:47], v[140:143], v[230:233], v[32:47]
	ds_read_b64_tr_b16 v[230:231], v202 offset:0x3600
	ds_read_b64_tr_b16 v[232:233], v202 offset:0x3e00
	s_waitcnt lgkmcnt(8)
	s_nop 0
	s_waitcnt lgkmcnt(0)
	v_mfma_f32_32x32x16_bf16 v[16:31], v[140:143], v[234:237], v[16:31]
	v_add_f32_e32 v140, 0, v112
	v_add_f32_e32 v140, v113, v140
	v_add_f32_e32 v140, v114, v140
	v_add_f32_e32 v140, v115, v140
	v_add_f32_e32 v140, v116, v140
	v_add_f32_e32 v140, v117, v140
	v_add_f32_e32 v140, v118, v140
	v_mfma_f32_32x32x16_bf16 v[0:15], v[164:167], v[144:147], v[0:15]
	v_add_f32_e32 v140, v119, v140
	v_add_f32_e32 v140, v120, v140
	v_add_f32_e32 v140, v121, v140
	v_add_f32_e32 v140, v122, v140
	v_add_f32_e32 v140, v123, v140
	v_add_f32_e32 v140, v124, v140
	v_add_f32_e32 v140, v125, v140
	v_mfma_f32_32x32x16_bf16 v[48:63], v[164:167], v[182:185], v[48:63]
	v_add_f32_e32 v140, v126, v140
	v_cvt_pk_bf16_f32 v144, v112, v113
	v_cvt_pk_bf16_f32 v145, v114, v115
	v_cvt_pk_bf16_f32 v146, v116, v117
	v_cvt_pk_bf16_f32 v147, v118, v119
	v_mfma_f32_32x32x16_bf16 v[32:47], v[164:167], v[186:189], v[32:47]
	v_mfma_f32_32x32x16_bf16 v[16:31], v[164:167], v[214:217], v[16:31]
	v_add_f32_e32 v164, v127, v140
	v_cvt_pk_bf16_f32 v140, v120, v121
	v_cvt_pk_bf16_f32 v141, v122, v123
	v_cvt_pk_bf16_f32 v142, v124, v125
	v_cvt_pk_bf16_f32 v143, v126, v127
	v_mfma_f32_32x32x16_bf16 v[0:15], v[160:163], v[218:221], v[0:15]
	s_waitcnt lgkmcnt(0)
	s_barrier
	v_mfma_f32_32x32x16_bf16 v[48:63], v[160:163], v[222:225], v[48:63]
	v_mfma_f32_32x32x16_bf16 v[32:47], v[160:163], v[226:229], v[32:47]
	v_mfma_f32_32x32x16_bf16 v[16:31], v[160:163], v[230:233], v[16:31]
	v_add_u32_e32 v202, s100, v202
	v_add_u32_e32 v203, s100, v203
	v_subrev_u32_e32 v205, s100, v205
	v_subrev_u32_e32 v206, s100, v206
	v_subrev_u32_e32 v207, s101, v207
	s_sub_i32 s100, 0, s100
	s_sub_i32 s101, 0, s101
	s_cbranch_vccnz .LBB0_411
	s_mov_b64 s[8:9], s[6:7]
	s_branch .LBB0_398

	.amdhsa_kernel _Z11mega_kernel6Paramsii
		.amdhsa_group_segment_fixed_size 16640
		.amdhsa_private_segment_fixed_size 0
		.amdhsa_kernarg_size 488
		.amdhsa_user_sgpr_count 2
		.amdhsa_user_sgpr_dispatch_ptr 0
		.amdhsa_user_sgpr_queue_ptr 0
		.amdhsa_user_sgpr_kernarg_segment_ptr 1
		.amdhsa_user_sgpr_dispatch_id 0
		.amdhsa_user_sgpr_kernarg_preload_length 0
		.amdhsa_user_sgpr_kernarg_preload_offset 0
		.amdhsa_user_sgpr_private_segment_size 0
		.amdhsa_uses_dynamic_stack 0
		.amdhsa_enable_private_segment 0
		.amdhsa_system_sgpr_workgroup_id_x 1
		.amdhsa_system_sgpr_workgroup_id_y 0
		.amdhsa_system_sgpr_workgroup_id_z 0
		.amdhsa_system_sgpr_workgroup_info 0
		.amdhsa_system_vgpr_workitem_id 2
		.amdhsa_next_free_vgpr 253
		.amdhsa_next_free_sgpr 102
		.amdhsa_accum_offset 256
		.amdhsa_reserve_vcc 1
		.amdhsa_float_round_mode_32 0
		.amdhsa_float_round_mode_16_64 0
		.amdhsa_float_denorm_mode_32 3
		.amdhsa_float_denorm_mode_16_64 3
		.amdhsa_dx10_clamp 1
		.amdhsa_ieee_mode 1
		.amdhsa_fp16_overflow 0
		.amdhsa_tg_split 0
		.amdhsa_exception_fp_ieee_invalid_op 0
		.amdhsa_exception_fp_denorm_src 0
		.amdhsa_exception_fp_ieee_div_zero 0
		.amdhsa_exception_fp_ieee_overflow 0
		.amdhsa_exception_fp_ieee_underflow 0
		.amdhsa_exception_fp_ieee_inexact 0
		.amdhsa_exception_int_div_zero 0
	.end_amdhsa_kernel

amdhsa.kernels:
  - .agpr_count:     0
    .args:
      - .offset:         0
        .size:           224
        .value_kind:     by_value
      - .offset:         224
        .size:           4
        .value_kind:     by_value
      - .offset:         228
        .size:           4
        .value_kind:     by_value
      - .offset:         232
        .size:           4
        .value_kind:     hidden_block_count_x
      - .offset:         236
        .size:           4
        .value_kind:     hidden_block_count_y
      - .offset:         240
        .size:           4
        .value_kind:     hidden_block_count_z
      - .offset:         244
        .size:           2
        .value_kind:     hidden_group_size_x
      - .offset:         246
        .size:           2
        .value_kind:     hidden_group_size_y
      - .offset:         248
        .size:           2
        .value_kind:     hidden_group_size_z
      - .offset:         250
        .size:           2
        .value_kind:     hidden_remainder_x
      - .offset:         252
        .size:           2
        .value_kind:     hidden_remainder_y
      - .offset:         254
        .size:           2
        .value_kind:     hidden_remainder_z
      - .offset:         272
        .size:           8
        .value_kind:     hidden_global_offset_x
      - .offset:         280
        .size:           8
        .value_kind:     hidden_global_offset_y
      - .offset:         288
        .size:           8
        .value_kind:     hidden_global_offset_z
      - .offset:         296
        .size:           2
        .value_kind:     hidden_grid_dims
      - .offset:         320
        .size:           8
        .value_kind:     hidden_multigrid_sync_arg
      - .offset:         352
        .size:           4
        .value_kind:     hidden_dynamic_lds_size
    .group_segment_fixed_size: 16640
    .kernarg_segment_align: 8
    .kernarg_segment_size: 488
    .language:       OpenCL C
    .language_version:
      - 2
      - 0
    .max_flat_workgroup_size: 512
    .name:           _Z11mega_kernel6Paramsii
    .private_segment_fixed_size: 0
    .sgpr_count:     108
    .sgpr_spill_count: 197
    .symbol:         _Z11mega_kernel6Paramsii.kd
    .uniform_work_group_size: 1
    .uses_dynamic_stack: false
    .vgpr_count:     253
    .vgpr_spill_count: 0
    .wavefront_size: 64
